# v9 = v7 + nt on the P1 weight-conversion 16B stores
# baseline (speedup 1.0000x reference)
; #define GAS __attribute__((address_space(1)))
; #define LAS __attribute__((address_space(3)))
; __device__ __forceinline__ void p0_convert(const P0Item& d, const LAS float* buf, int w, int lane, bool NT) {
;     if (d.f8) {
;         const int c = lane & 3;
; #pragma unroll
;         for (int j = 0; j < 2; ++j) { const int n = (lane >> 2) + 16 * j; const LAS float* s = buf + (16 * c) * TPITCH + 32 * w + n;
;             v4u o; o.x = pg8::pk4_fp8(s[0 * TPITCH], s[1 * TPITCH], s[2 * TPITCH], s[3 * TPITCH]); o.y = pg8::pk4_fp8(s[4 * TPITCH], s[5 * TPITCH], s[6 * TPITCH], s[7 * TPITCH]);
;             o.z = pg8::pk4_fp8(s[8 * TPITCH], s[9 * TPITCH], s[10 * TPITCH], s[11 * TPITCH]); o.w = pg8::pk4_fp8(s[12 * TPITCH], s[13 * TPITCH], s[14 * TPITCH], s[15 * TPITCH]);
;             if (NT) __builtin_nontemporal_store(o, (v4u*)(d.dst + (size_t)n * d.ldkb + 16 * c)); else *(GAS v4u*)(d.dst + (size_t)n * d.ldkb + 16 * c) = o; }
.LBB0_189:
	s_or_b64 exec, exec, s[0:1]
	s_cmp_eq_u32 s67, 0
	s_cselect_b64 s[22:23], -1, 0
	s_and_b64 s[0:1], s[22:23], exec
	s_cselect_b32 s24, 0, s54
	s_cmp_eq_u32 s34, 0
	s_cbranch_scc1 .LBB0_197
	s_add_i32 s0, s64, s24
	v_lshlrev_b32_e32 v34, 2, v40
	v_add3_u32 v37, s0, v47, v34
	ds_read2_b32 v[56:57], v37 offset1:16
	v_add_u32_e32 v34, 0x400, v37
	ds_read2_b32 v[58:59], v34 offset0:4 offset1:20
	v_add_u32_e32 v34, 0x800, v37
	ds_read2_b32 v[60:61], v34 offset0:8 offset1:24
	v_add_u32_e32 v34, 0xc00, v37
	ds_read2_b32 v[62:63], v34 offset0:12 offset1:28
	s_waitcnt lgkmcnt(3)
	v_max_f32_e32 v34, v56, v56
	v_med3_f32 v35, v34, s55, v53
	s_waitcnt lgkmcnt(2)
	v_max_f32_e32 v34, v58, v58
	v_med3_f32 v36, v34, s55, v53
	v_mov_b32_e32 v34, 0
	v_cvt_pk_fp8_f32 v34, v35, v36
	s_waitcnt lgkmcnt(1)
	v_max_f32_e32 v35, v60, v60
	s_waitcnt lgkmcnt(0)
	v_max_f32_e32 v36, v62, v62
	v_med3_f32 v35, v35, s55, v53
	v_med3_f32 v36, v36, s55, v53
	v_cvt_pk_fp8_f32 v34, v35, v36 op_sel:[0,0,1]
	v_add_u32_e32 v35, 0x1000, v37
	ds_read2_b32 v[64:65], v35 offset0:16 offset1:32
	v_add_u32_e32 v35, 0x1400, v37
	ds_read2_b32 v[66:67], v35 offset0:20 offset1:36
	v_add_u32_e32 v35, 0x1800, v37
	ds_read2_b32 v[68:69], v35 offset0:24 offset1:40
	v_add_u32_e32 v35, 0x1c00, v37
	ds_read2_b32 v[70:71], v35 offset0:28 offset1:44
	s_waitcnt lgkmcnt(3)
	v_max_f32_e32 v35, v64, v64
	v_med3_f32 v36, v35, s55, v53
	s_waitcnt lgkmcnt(2)
	v_max_f32_e32 v35, v66, v66
	v_med3_f32 v55, v35, s55, v53
	v_mov_b32_e32 v35, 0
	v_cvt_pk_fp8_f32 v35, v36, v55
	s_waitcnt lgkmcnt(1)
	v_max_f32_e32 v36, v68, v68
	s_waitcnt lgkmcnt(0)
	v_max_f32_e32 v55, v70, v70
	v_med3_f32 v36, v36, s55, v53
	v_med3_f32 v55, v55, s55, v53
	v_cvt_pk_fp8_f32 v35, v36, v55 op_sel:[0,0,1]
	v_add_u32_e32 v36, 0x2000, v37
	ds_read2_b32 v[72:73], v36 offset0:32 offset1:48
	v_add_u32_e32 v36, 0x2400, v37
	ds_read2_b32 v[74:75], v36 offset0:36 offset1:52
	v_add_u32_e32 v36, 0x2800, v37
	ds_read2_b32 v[76:77], v36 offset0:40 offset1:56
	v_add_u32_e32 v36, 0x2c00, v37
	ds_read2_b32 v[78:79], v36 offset0:44 offset1:60
	s_waitcnt lgkmcnt(3)
	v_max_f32_e32 v36, v72, v72
	v_med3_f32 v55, v36, s55, v53
	s_waitcnt lgkmcnt(2)
	v_max_f32_e32 v36, v74, v74
	v_med3_f32 v56, v36, s55, v53
	v_mov_b32_e32 v36, 0
	v_cvt_pk_fp8_f32 v36, v55, v56
	s_waitcnt lgkmcnt(1)
	v_max_f32_e32 v55, v76, v76
	s_waitcnt lgkmcnt(0)
	v_max_f32_e32 v56, v78, v78
	v_med3_f32 v55, v55, s55, v53
	v_med3_f32 v56, v56, s55, v53
	v_cvt_pk_fp8_f32 v36, v55, v56 op_sel:[0,0,1]
	v_add_u32_e32 v55, 0x3000, v37
	ds_read2_b32 v[80:81], v55 offset0:48 offset1:64
	v_add_u32_e32 v55, 0x3400, v37
	ds_read2_b32 v[82:83], v55 offset0:52 offset1:68
	v_add_u32_e32 v55, 0x3800, v37
	v_add_u32_e32 v37, 0x3c00, v37
	ds_read2_b32 v[84:85], v55 offset0:56 offset1:72
	ds_read2_b32 v[86:87], v37 offset0:60 offset1:76
	s_waitcnt lgkmcnt(3)
	v_max_f32_e32 v37, v80, v80
	v_med3_f32 v55, v37, s55, v53
	s_waitcnt lgkmcnt(2)
	v_max_f32_e32 v37, v82, v82
	v_med3_f32 v56, v37, s55, v53
	v_mov_b32_e32 v37, 0
	v_cvt_pk_fp8_f32 v37, v55, v56
	s_waitcnt lgkmcnt(1)
	v_max_f32_e32 v55, v84, v84
	s_waitcnt lgkmcnt(0)
	v_max_f32_e32 v56, v86, v86
	v_med3_f32 v55, v55, s55, v53
	v_med3_f32 v56, v56, s55, v53
	v_cvt_pk_fp8_f32 v37, v55, v56 op_sel:[0,0,1]
	v_mov_b64_e32 v[88:89], s[16:17]
	v_mad_i64_i32 v[88:89], s[0:1], s53, v40, v[88:89]
	v_lshl_add_u64 v[88:89], v[88:89], 0, v[42:43]
	global_store_dwordx4 v[88:89], v[34:37], off nt
	s_nop 1
	v_max_f32_e32 v34, v57, v57
	v_med3_f32 v35, v34, s55, v53
	v_max_f32_e32 v34, v59, v59
	v_med3_f32 v36, v34, s55, v53
	v_mov_b32_e32 v34, 0
	v_cvt_pk_fp8_f32 v34, v35, v36
	v_max_f32_e32 v35, v61, v61
	v_max_f32_e32 v36, v63, v63
	v_med3_f32 v35, v35, s55, v53
	v_med3_f32 v36, v36, s55, v53
	v_cvt_pk_fp8_f32 v34, v35, v36 op_sel:[0,0,1]
	v_max_f32_e32 v35, v65, v65
	v_med3_f32 v36, v35, s55, v53
	v_max_f32_e32 v35, v67, v67
	v_med3_f32 v37, v35, s55, v53
	v_mov_b32_e32 v35, 0
	v_cvt_pk_fp8_f32 v35, v36, v37
	v_max_f32_e32 v36, v69, v69
	v_max_f32_e32 v37, v71, v71
	v_med3_f32 v36, v36, s55, v53
	v_med3_f32 v37, v37, s55, v53
	v_cvt_pk_fp8_f32 v35, v36, v37 op_sel:[0,0,1]
	v_max_f32_e32 v36, v73, v73
	v_med3_f32 v37, v36, s55, v53
	v_max_f32_e32 v36, v75, v75
	v_med3_f32 v55, v36, s55, v53
	v_mov_b32_e32 v36, 0
	v_cvt_pk_fp8_f32 v36, v37, v55
	v_max_f32_e32 v37, v77, v77
	v_max_f32_e32 v55, v79, v79
	v_med3_f32 v37, v37, s55, v53
	v_med3_f32 v55, v55, s55, v53
	v_cvt_pk_fp8_f32 v36, v37, v55 op_sel:[0,0,1]
	v_max_f32_e32 v37, v81, v81
	v_med3_f32 v55, v37, s55, v53
	v_max_f32_e32 v37, v83, v83
	v_med3_f32 v56, v37, s55, v53
	v_mov_b32_e32 v37, 0
	v_cvt_pk_fp8_f32 v37, v55, v56
	v_max_f32_e32 v55, v85, v85
	v_max_f32_e32 v56, v87, v87
	v_med3_f32 v55, v55, s55, v53
	v_med3_f32 v56, v56, s55, v53
	v_cvt_pk_fp8_f32 v37, v55, v56 op_sel:[0,0,1]
	v_mad_i64_i32 v[56:57], s[0:1], s53, v44, 0
	v_mov_b64_e32 v[58:59], v[42:43]
	s_cbranch_execnz .LBB0_192
; #define GAS __attribute__((address_space(1)))
; #define LAS __attribute__((address_space(3)))
; __device__ __forceinline__ unsigned pk2(float lo, float hi) { return f2bf(lo) | (f2bf(hi) << 16); }
; __device__ __forceinline__ void tile_store(LAS float* buf, const f32x4 (&t)[8], float mul, int w, int lane) {
; #pragma unroll
;     for (int i = 0; i < 8; ++i) *(LAS f32x4*)(buf + (8 * w + i) * TPITCH + 4 * lane) = t[i] * mul;
; __device__ __forceinline__ void p0_convert(const P0Item& d, const LAS float* buf, int w, int lane, bool NT) {
;     ...
;     } else {
;         const int c = lane & 7;
; #pragma unroll
;         for (int j = 0; j < 4; ++j) { const int n = (lane >> 3) + 8 * j; const LAS float* s = buf + (8 * c) * TPITCH + 32 * w + n;
;             v4u o; o.x = pk2(s[0 * TPITCH], s[1 * TPITCH]); o.y = pk2(s[2 * TPITCH], s[3 * TPITCH]); o.z = pk2(s[4 * TPITCH], s[5 * TPITCH]); o.w = pk2(s[6 * TPITCH], s[7 * TPITCH]);
;             if (NT) __builtin_nontemporal_store(o, (v4u*)(d.dst + (size_t)n * d.ldkb + 16 * c)); else *(GAS v4u*)(d.dst + (size_t)n * d.ldkb + 16 * c) = o; }
;     }
.LBB0_191:
	s_add_i32 s0, s64, s24
	v_lshlrev_b32_e32 v34, 2, v46
	v_add3_u32 v55, s0, v51, v34
	ds_read2_b32 v[56:57], v55 offset1:8
	v_add_u32_e32 v76, 0x400, v55
	ds_read2_b32 v[58:59], v76 offset0:4 offset1:12
	v_add_u32_e32 v77, 0x800, v55
	ds_read2_b32 v[60:61], v77 offset0:8 offset1:16
	v_add_u32_e32 v78, 0xc00, v55
	ds_read2_b32 v[62:63], v78 offset0:12 offset1:20
	s_waitcnt lgkmcnt(3)
	v_bfe_u32 v34, v56, 16, 1
	v_add_u32_e32 v79, 0x1000, v55
	v_add3_u32 v34, v56, v34, s65
	s_waitcnt lgkmcnt(2)
	v_bfe_u32 v35, v58, 16, 1
	ds_read2_b32 v[64:65], v79 offset0:16 offset1:24
	v_add_u32_e32 v80, 0x1400, v55
	v_lshrrev_b32_e32 v34, 16, v34
	v_add3_u32 v35, v58, v35, s65
	ds_read2_b32 v[66:67], v80 offset0:20 offset1:28
	v_and_or_b32 v34, v35, s66, v34
	s_waitcnt lgkmcnt(3)
	v_bfe_u32 v35, v60, 16, 1
	v_add_u32_e32 v81, 0x1800, v55
	v_add3_u32 v35, v60, v35, s65
	s_waitcnt lgkmcnt(2)
	v_bfe_u32 v36, v62, 16, 1
	ds_read2_b32 v[68:69], v81 offset0:24 offset1:32
	v_add_u32_e32 v82, 0x1c00, v55
	v_lshrrev_b32_e32 v35, 16, v35
	v_add3_u32 v36, v62, v36, s65
	ds_read2_b32 v[70:71], v82 offset0:28 offset1:36
	v_and_or_b32 v35, v36, s66, v35
	s_waitcnt lgkmcnt(3)
	v_bfe_u32 v36, v64, 16, 1
	v_add3_u32 v36, v64, v36, s65
	s_waitcnt lgkmcnt(2)
	v_bfe_u32 v37, v66, 16, 1
	v_lshrrev_b32_e32 v36, 16, v36
	v_add3_u32 v37, v66, v37, s65
	v_and_or_b32 v36, v37, s66, v36
	s_waitcnt lgkmcnt(1)
	v_bfe_u32 v37, v68, 16, 1
	v_add3_u32 v37, v68, v37, s65
	s_waitcnt lgkmcnt(0)
	v_bfe_u32 v56, v70, 16, 1
	v_mov_b64_e32 v[72:73], s[16:17]
	v_lshrrev_b32_e32 v37, 16, v37
	v_add3_u32 v56, v70, v56, s65
	v_mad_i64_i32 v[74:75], s[0:1], s53, v46, v[72:73]
	v_and_or_b32 v37, v56, s66, v37
	v_lshl_add_u64 v[74:75], v[74:75], 0, v[48:49]
	global_store_dwordx4 v[74:75], v[34:37], off nt
	v_bfe_u32 v56, v71, 16, 1
	v_add3_u32 v56, v71, v56, s65
	v_bfe_u32 v34, v57, 16, 1
	v_add3_u32 v34, v57, v34, s65
	v_bfe_u32 v35, v59, 16, 1
	v_lshrrev_b32_e32 v34, 16, v34
	v_add3_u32 v35, v59, v35, s65
	v_and_or_b32 v34, v35, s66, v34
	v_bfe_u32 v35, v61, 16, 1
	v_add3_u32 v35, v61, v35, s65
	v_bfe_u32 v36, v63, 16, 1
	v_lshrrev_b32_e32 v35, 16, v35
	v_add3_u32 v36, v63, v36, s65
	v_and_or_b32 v35, v36, s66, v35
	v_bfe_u32 v36, v65, 16, 1
	v_add3_u32 v36, v65, v36, s65
	v_bfe_u32 v37, v67, 16, 1
	v_lshrrev_b32_e32 v36, 16, v36
	v_add3_u32 v37, v67, v37, s65
	v_and_or_b32 v36, v37, s66, v36
	v_bfe_u32 v37, v69, 16, 1
	v_add3_u32 v37, v69, v37, s65
	v_lshrrev_b32_e32 v37, 16, v37
	v_mad_i64_i32 v[58:59], s[0:1], s53, v50, v[72:73]
	v_and_or_b32 v37, v56, s66, v37
	ds_read2_b32 v[56:57], v55 offset0:16 offset1:24
	v_lshl_add_u64 v[58:59], v[58:59], 0, v[48:49]
	global_store_dwordx4 v[58:59], v[34:37], off nt
	ds_read2_b32 v[58:59], v76 offset0:20 offset1:28
	ds_read2_b32 v[60:61], v77 offset0:24 offset1:32
	ds_read2_b32 v[62:63], v78 offset0:28 offset1:36
	s_waitcnt lgkmcnt(3)
	v_bfe_u32 v34, v56, 16, 1
	v_add3_u32 v34, v56, v34, s65
	s_waitcnt lgkmcnt(2)
	v_bfe_u32 v35, v58, 16, 1
	ds_read2_b32 v[64:65], v79 offset0:32 offset1:40
	v_lshrrev_b32_e32 v34, 16, v34
	v_add3_u32 v35, v58, v35, s65
	ds_read2_b32 v[66:67], v80 offset0:36 offset1:44
	v_and_or_b32 v34, v35, s66, v34
	s_waitcnt lgkmcnt(3)
	v_bfe_u32 v35, v60, 16, 1
	v_add3_u32 v35, v60, v35, s65
	s_waitcnt lgkmcnt(2)
	v_bfe_u32 v36, v62, 16, 1
	ds_read2_b32 v[68:69], v81 offset0:40 offset1:48
	v_lshrrev_b32_e32 v35, 16, v35
	v_add3_u32 v36, v62, v36, s65
	ds_read2_b32 v[70:71], v82 offset0:44 offset1:52
	v_and_or_b32 v35, v36, s66, v35
	s_waitcnt lgkmcnt(3)
	v_bfe_u32 v36, v64, 16, 1
	v_add3_u32 v36, v64, v36, s65
	s_waitcnt lgkmcnt(2)
	v_bfe_u32 v37, v66, 16, 1
	v_lshrrev_b32_e32 v36, 16, v36
	v_add3_u32 v37, v66, v37, s65
	v_and_or_b32 v36, v37, s66, v36
	s_waitcnt lgkmcnt(1)
	v_bfe_u32 v37, v68, 16, 1
	v_add3_u32 v37, v68, v37, s65
	s_waitcnt lgkmcnt(0)
	v_bfe_u32 v55, v70, 16, 1
	v_lshrrev_b32_e32 v37, 16, v37
	v_add3_u32 v55, v70, v55, s65
	v_mad_i64_i32 v[72:73], s[0:1], s53, v52, v[72:73]
	v_and_or_b32 v37, v55, s66, v37
	v_lshl_add_u64 v[72:73], v[72:73], 0, v[48:49]
	global_store_dwordx4 v[72:73], v[34:37], off nt
	v_bfe_u32 v55, v71, 16, 1
	v_add3_u32 v55, v71, v55, s65
	v_bfe_u32 v34, v57, 16, 1
	v_add3_u32 v34, v57, v34, s65
	v_bfe_u32 v35, v59, 16, 1
	v_lshrrev_b32_e32 v34, 16, v34
	v_add3_u32 v35, v59, v35, s65
	v_and_or_b32 v34, v35, s66, v34
	v_bfe_u32 v35, v61, 16, 1
	v_add3_u32 v35, v61, v35, s65
	v_bfe_u32 v36, v63, 16, 1
	v_lshrrev_b32_e32 v35, 16, v35
	v_add3_u32 v36, v63, v36, s65
	v_and_or_b32 v35, v36, s66, v35
	v_bfe_u32 v36, v65, 16, 1
	v_add3_u32 v36, v65, v36, s65
	v_bfe_u32 v37, v67, 16, 1
	v_lshrrev_b32_e32 v36, 16, v36
	v_add3_u32 v37, v67, v37, s65
	v_and_or_b32 v36, v37, s66, v36
	v_bfe_u32 v37, v69, 16, 1
	v_add3_u32 v37, v69, v37, s65
	v_lshrrev_b32_e32 v37, 16, v37
	v_and_or_b32 v37, v55, s66, v37
	v_mad_i64_i32 v[56:57], s[0:1], s53, v54, 0
	v_mov_b64_e32 v[58:59], v[48:49]
.LBB0_192:
	v_lshl_add_u64 v[56:57], s[16:17], 0, v[56:57]
	v_cndmask_b32_e64 v55, 0, 1, s[18:19]
	v_lshl_add_u64 v[56:57], v[56:57], 0, v[58:59]
	v_cmp_ne_u32_e64 s[0:1], 1, v55
	s_andn2_b64 vcc, exec, s[18:19]
	global_store_dwordx4 v[56:57], v[34:37], off nt
	s_cbranch_vccnz .LBB0_194
	s_and_b64 s[16:17], s[22:23], exec
	s_cselect_b32 s16, s54, 0
	s_add_i32 s16, s63, s16
	s_waitcnt vmcnt(8)
	v_pk_mul_f32 v[36:37], s[14:15], v[4:5] op_sel_hi:[0,1]
	v_pk_mul_f32 v[34:35], s[14:15], v[2:3] op_sel_hi:[0,1]
	v_add_u32_e32 v55, s16, v45
	ds_write_b128 v55, v[34:37]
	s_waitcnt vmcnt(7)
	v_pk_mul_f32 v[36:37], s[14:15], v[8:9] op_sel_hi:[0,1]
	v_pk_mul_f32 v[34:35], s[14:15], v[6:7] op_sel_hi:[0,1]
	ds_write_b128 v55, v[34:37] offset:1040
	s_waitcnt vmcnt(6)
	v_pk_mul_f32 v[36:37], s[14:15], v[12:13] op_sel_hi:[0,1]
	v_pk_mul_f32 v[34:35], s[14:15], v[10:11] op_sel_hi:[0,1]
	ds_write_b128 v55, v[34:37] offset:2080
	s_waitcnt vmcnt(5)
	v_pk_mul_f32 v[36:37], s[14:15], v[16:17] op_sel_hi:[0,1]
	v_pk_mul_f32 v[34:35], s[14:15], v[14:15] op_sel_hi:[0,1]
	ds_write_b128 v55, v[34:37] offset:3120
	s_waitcnt vmcnt(4)
	v_pk_mul_f32 v[36:37], s[14:15], v[20:21] op_sel_hi:[0,1]
	v_pk_mul_f32 v[34:35], s[14:15], v[18:19] op_sel_hi:[0,1]
	ds_write_b128 v55, v[34:37] offset:4160
	s_waitcnt vmcnt(3)
	v_pk_mul_f32 v[36:37], s[14:15], v[24:25] op_sel_hi:[0,1]
	v_pk_mul_f32 v[34:35], s[14:15], v[22:23] op_sel_hi:[0,1]
	ds_write_b128 v55, v[34:37] offset:5200
	s_waitcnt vmcnt(2)
	v_pk_mul_f32 v[36:37], s[14:15], v[28:29] op_sel_hi:[0,1]
	v_pk_mul_f32 v[34:35], s[14:15], v[26:27] op_sel_hi:[0,1]
	ds_write_b128 v55, v[34:37] offset:6240
	s_waitcnt vmcnt(1)
	v_pk_mul_f32 v[36:37], s[14:15], v[32:33] op_sel_hi:[0,1]
	v_pk_mul_f32 v[34:35], s[14:15], v[30:31] op_sel_hi:[0,1]
	s_mov_b32 s34, s74
	s_mov_b32 s53, s80
	s_mov_b64 s[16:17], s[20:21]
	s_mov_b32 s31, s75
	ds_write_b128 v55, v[34:37] offset:7280
